# SSD prefetch: wave 0's dt loads issued first in the group; its scan waits vmcnt(14) instead of draining the prefetch
# speedup vs baseline: 1.0059x; 1.0044x over previous
; __device__ __forceinline__ float silu_f(float x) { return x * sigm(x); }
; #define LAS __attribute__((address_space(3)))
; __device__ __forceinline__ void ssd_stream(const Frame& F, const Args& A, int sidx) {
;     ...
;                 for (int k = 0; k < 4; ++k) { const int lr = (lane >> 3) + k - 3;
;                     LAS unsigned char* src = lr >= 0 ? XST + (8 * w + lr + 64 * i) * XS_ + 16 * (lane & 7) : HAL + (3 * i + 3 + lr) * XS_ + 16 * (lane & 7);
;                     rw[i][k] = *(LAS v4u*)src; }
;             f32x4 cwa[5], cwb[5];
; #pragma unroll
;             for (int k = 0; k < 5; ++k) { cwa[k] = *(LAS f32x4*)(CWL + 64 * k + 8 * (lane & 7)); cwb[k] = *(LAS f32x4*)(CWL + 64 * k + 8 * (lane & 7) + 4); }
;             asm volatile("s_waitcnt lgkmcnt(0)" ::: "memory");
; #pragma unroll
;             for (int i = 0; i < 2; ++i) {
;                 const int row = (tid >> 3) + 64 * i;
;                 float y[8];
; #pragma unroll
;                 for (int e = 0; e < 8; ++e) y[e] = e < 4 ? cwa[4][e] : cwb[4][e - 4];
; #pragma unroll
;                 for (int k = 0; k < 4; ++k) { const v4u r = rw[i][k];
;                     y[0] += cwa[k][0] * bflo(r.x); y[1] += cwa[k][1] * bfhi(r.x); y[2] += cwa[k][2] * bflo(r.y); y[3] += cwa[k][3] * bfhi(r.y);
;                     y[4] += cwb[k][0] * bflo(r.z); y[5] += cwb[k][1] * bfhi(r.z); y[6] += cwb[k][2] * bflo(r.w); y[7] += cwb[k][3] * bfhi(r.w); }
; #pragma unroll
;                 for (int e = 0; e < 8; ++e) y[e] = silu_f(y[e]);
;                 *(LAS bf16x8*)(XT + xdst + 64 * i * XS_) = packf8(y[0], y[1], y[2], y[3], y[4], y[5], y[6], y[7]);
.LBB0_1297:
	s_or_b64 exec, exec, s[26:27]
	ds_read_b128 v[108:111], v212
	ds_read_b128 v[112:115], v213
	ds_read_b128 v[116:119], v214
	ds_read_b128 v[120:123], v215
	ds_read_b128 v[34:37], v216
	ds_read_b128 v[38:41], v217
	ds_read_b128 v[22:25], v218
	ds_read_b128 v[26:29], v219
	ds_read_b128 v[98:101], v207
	ds_read_b128 v[42:45], v207 offset:16
	ds_read_b128 v[124:127], v207 offset:256
	ds_read_b128 v[128:131], v207 offset:272
	ds_read_b128 v[30:33], v207 offset:512
	ds_read_b128 v[18:21], v207 offset:528
	ds_read_b128 v[132:135], v207 offset:768
	ds_read_b128 v[190:193], v207 offset:784
	ds_read_b128 v[102:105], v207 offset:1024
	ds_read_b128 v[46:49], v207 offset:1040
	s_waitcnt lgkmcnt(14)
	v_lshlrev_b32_e32 v137, 16, v108
	v_lshlrev_b32_e32 v136, 16, v112
	s_waitcnt lgkmcnt(7)
	v_mov_b32_e32 v194, v124
	v_mov_b32_e32 v195, v98
	s_waitcnt lgkmcnt(0)
	v_lshl_add_u32 v107, v175, 2, s78
	s_waitcnt lgkmcnt(1)
	v_fma_f32 v98, v98, v137, v102
	v_fma_f32 v140, v124, v136, v98
	v_and_b32_e32 v137, 0xffff0000, v108
	v_and_b32_e32 v136, 0xffff0000, v112
	v_mov_b32_e32 v98, v125
	v_fma_f32 v108, v99, v137, v103
	v_fma_f32 v196, v125, v136, v108
	v_lshlrev_b32_e32 v125, 16, v109
	v_lshlrev_b32_e32 v124, 16, v113
	v_mov_b32_e32 v137, v100
	v_and_b32_e32 v109, 0xffff0000, v109
	v_fma_f32 v100, v100, v125, v104
	v_fma_f32 v197, v126, v124, v100
	v_and_b32_e32 v108, 0xffff0000, v113
	v_mov_b32_e32 v100, v127
	v_mov_b32_e32 v112, v128
	v_fma_f32 v109, v101, v109, v105
	v_fma_f32 v186, v127, v108, v109
	v_lshlrev_b32_e32 v109, 16, v110
	v_lshlrev_b32_e32 v108, 16, v114
	v_mov_b32_e32 v113, v42
	v_mov_b32_e32 v124, v130
	s_waitcnt lgkmcnt(0)
	v_fma_f32 v42, v42, v109, v46
	v_fma_f32 v128, v128, v108, v42
	v_and_b32_e32 v109, 0xffff0000, v110
	v_and_b32_e32 v108, 0xffff0000, v114
	v_mov_b32_e32 v42, v129
	v_mov_b32_e32 v125, v44
	v_fma_f32 v109, v43, v109, v47
	v_fma_f32 v110, v129, v108, v109
	v_lshlrev_b32_e32 v109, 16, v111
	v_lshlrev_b32_e32 v108, 16, v115
	v_mov_b32_e32 v114, v132
	v_fma_f32 v44, v44, v109, v48
	v_fma_f32 v129, v130, v108, v44
	v_and_b32_e32 v109, 0xffff0000, v111
	v_and_b32_e32 v108, 0xffff0000, v115
	v_mov_b32_e32 v44, v131
	v_mov_b32_e32 v115, v30
	v_fma_f32 v109, v45, v109, v49
	v_fma_f32 v111, v131, v108, v109
	v_lshlrev_b32_e32 v109, 16, v116
	v_lshlrev_b32_e32 v108, 16, v120
	v_fma_f32 v30, v30, v109, v140
	v_fma_f32 v130, v132, v108, v30
	v_and_b32_e32 v109, 0xffff0000, v116
	v_and_b32_e32 v108, 0xffff0000, v120
	v_mov_b32_e32 v30, v133
	v_mov_b32_e32 v127, v32
	v_fma_f32 v109, v31, v109, v196
	v_fma_f32 v131, v133, v108, v109
	v_lshlrev_b32_e32 v109, 16, v117
	v_lshlrev_b32_e32 v108, 16, v121
	v_fma_f32 v32, v32, v109, v197
	v_fma_f32 v132, v134, v108, v32
	v_and_b32_e32 v109, 0xffff0000, v117
	v_and_b32_e32 v108, 0xffff0000, v121
	v_mov_b32_e32 v117, v18
	v_fma_f32 v109, v33, v109, v186
	v_fma_f32 v133, v135, v108, v109
	v_lshlrev_b32_e32 v109, 16, v118
	v_lshlrev_b32_e32 v108, 16, v122
	v_fma_f32 v18, v18, v109, v128
	v_fma_f32 v128, v190, v108, v18
	v_and_b32_e32 v109, 0xffff0000, v118
	v_and_b32_e32 v108, 0xffff0000, v122
	v_mov_b32_e32 v121, v20
	v_fma_f32 v109, v19, v109, v110
	v_fma_f32 v110, v191, v108, v109
	v_lshlrev_b32_e32 v109, 16, v119
	v_lshlrev_b32_e32 v108, 16, v123
	v_mul_f32_e32 v122, 0xbfb8aa3b, v133
	v_fma_f32 v20, v20, v109, v129
	v_fma_f32 v118, v192, v108, v20
	v_and_b32_e32 v109, 0xffff0000, v119
	v_and_b32_e32 v108, 0xffff0000, v123
	v_mov_b32_e32 v20, v193
	v_mul_f32_e32 v119, 0xbfb8aa3b, v130
	v_fma_f32 v109, v21, v109, v111
	v_mul_f32_e32 v111, 0xbfb8aa3b, v131
	v_exp_f32_e32 v119, v119
	v_exp_f32_e32 v111, v111
	v_fma_f32 v108, v193, v108, v109
	v_exp_f32_e32 v122, v122
	v_add_f32_e32 v109, 1.0, v119
	v_add_f32_e32 v111, 1.0, v111
	v_rcp_f32_e32 v109, v109
	v_rcp_f32_e32 v111, v111
	v_mul_f32_e32 v119, 0xbfb8aa3b, v132
	v_exp_f32_e32 v119, v119
	v_mul_f32_e32 v123, v130, v109
	v_mul_f32_e32 v129, v131, v111
	v_add_f32_e32 v109, 1.0, v122
	v_mul_f32_e32 v111, 0xbfb8aa3b, v128
	v_mul_f32_e32 v122, 0xbfb8aa3b, v110
	v_rcp_f32_e32 v109, v109
	v_exp_f32_e32 v111, v111
	v_exp_f32_e32 v122, v122
	v_mul_f32_e32 v131, 0xbfb8aa3b, v108
	v_mul_f32_e32 v130, v133, v109
	v_add_f32_e32 v109, 1.0, v111
	v_add_f32_e32 v111, 1.0, v122
	v_mul_f32_e32 v122, 0xbfb8aa3b, v118
	v_exp_f32_e32 v122, v122
	v_exp_f32_e32 v131, v131
	v_add_f32_e32 v119, 1.0, v119
	v_rcp_f32_e32 v119, v119
	v_add_f32_e32 v122, 1.0, v122
	v_add_f32_e32 v131, 1.0, v131
	v_rcp_f32_e32 v109, v109
	v_rcp_f32_e32 v111, v111
	v_rcp_f32_e32 v122, v122
	v_rcp_f32_e32 v131, v131
	v_mul_f32_e32 v119, v132, v119
	v_mul_f32_e32 v128, v128, v109
	v_mul_f32_e32 v132, v110, v111
	v_mul_f32_e32 v118, v118, v122
	v_mul_f32_e32 v122, v108, v131
	v_cvt_pk_bf16_f32 v108, v123, v129
	v_cvt_pk_bf16_f32 v109, v119, v130
	v_cvt_pk_bf16_f32 v110, v128, v132
	v_cvt_pk_bf16_f32 v111, v118, v122
	ds_write_b128 v229, v[108:111]
	ds_read2st64_b32 v[108:109], v107 offset1:2
	s_cmp_lg_u32 s5, 63
	s_cselect_b64 s[60:61], -1, 0
	s_waitcnt lgkmcnt(0)
; __device__ __forceinline__ float ex2(float x) { return __builtin_amdgcn_exp2f(x); }
; #define GAS __attribute__((address_space(1)))
; #define LAS __attribute__((address_space(3)))
; __device__ __forceinline__ void ssd_stream(const Frame& F, const Args& A, int sidx) {
;     ...
;                 const float te = ex2(aL - arr[row]) * arr[128 + row];
;                 *(LAS bf16x8*)(XST + xdst + 64 * i * XS_) = packf8(y[0] * te, y[1] * te, y[2] * te, y[3] * te, y[4] * te, y[5] * te, y[6] * te, y[7] * te);
;             }
; #pragma unroll
;             for (int i = 0; i < 4; ++i) { *(LAS v4u*)(BT + bdst + 32 * i * BS_) = pfb[i]; *(LAS v4u*)(CT + bdst + 32 * i * BS_) = pfc[i]; }
;         }
;         v2u zw[4];
;         { const GAS unsigned char* zb = Zg + (size_t)t0 * 4096;
; #pragma unroll
;           for (int q4 = 0; q4 < 4; ++q4) zw[q4] = *(const GAS v2u*)(zb + 16 * q4 + zoff); }
;         if (ck < 63) {
;             const GAS unsigned char* xb = XCg + (size_t)(t0 + 128) * 6144; const GAS unsigned char* rb = XBg + (size_t)(t0 + 128) * 6144;
; #pragma unroll
;             for (int i = 0; i < 2; ++i) { pfx[i] = *(const GAS v4u*)(rb + (size_t)i * (64 * 6144) + xoff);
;                 if (lane < 24) pfh[i] = *(const GAS v4u*)(rb + (ptrdiff_t)(hrow + 64 * i) * 6144 + hoff); }
; #pragma unroll
;             for (int i = 0; i < 4; ++i) { pfb[i] = *(const GAS v4u*)(xb + (size_t)i * (32 * 6144) + boff); pfc[i] = *(const GAS v4u*)(xb + (size_t)i * (32 * 6144) + 1024 + boff); }
;             if (w == 0) { const GAS unsigned char* db = DTg + (size_t)(t0 + 128) * 128; pd0 = *(const GAS float*)(db + doff); pd1 = *(const GAS float*)(db + 128 + doff); }
	v_sub_f32_e32 v108, v106, v108
	v_exp_f32_e32 v108, v108
	s_cmp_eq_u32 s5, 63
	v_mul_f32_e32 v108, v109, v108
	v_mul_f32_e32 v109, v123, v108
	v_mul_f32_e32 v110, v129, v108
	v_mul_f32_e32 v111, v119, v108
	v_mul_f32_e32 v119, v130, v108
	v_mul_f32_e32 v123, v128, v108
	v_mul_f32_e32 v128, v132, v108
	v_mul_f32_e32 v118, v118, v108
	v_mul_f32_e32 v122, v122, v108
	v_cvt_pk_bf16_f32 v108, v109, v110
	v_cvt_pk_bf16_f32 v109, v111, v119
	v_cvt_pk_bf16_f32 v110, v123, v128
	v_cvt_pk_bf16_f32 v111, v118, v122
	ds_write_b128 v229, v[108:111] offset:18432
	v_lshlrev_b32_e32 v109, 16, v34
	v_lshlrev_b32_e32 v108, 16, v38
	v_fma_f32 v102, v195, v109, v102
	v_fma_f32 v102, v194, v108, v102
	v_and_b32_e32 v109, 0xffff0000, v34
	v_and_b32_e32 v108, 0xffff0000, v38
	v_fma_f32 v34, v99, v109, v103
	v_fma_f32 v38, v98, v108, v34
	v_lshlrev_b32_e32 v99, 16, v35
	v_lshlrev_b32_e32 v98, 16, v39
	v_and_b32_e32 v35, 0xffff0000, v35
	v_fma_f32 v34, v137, v99, v104
	v_fma_f32 v98, v126, v98, v34
	v_and_b32_e32 v34, 0xffff0000, v39
	v_fma_f32 v35, v101, v35, v105
	v_fma_f32 v39, v100, v34, v35
	v_lshlrev_b32_e32 v35, 16, v36
	v_lshlrev_b32_e32 v34, 16, v40
	v_fma_f32 v35, v113, v35, v46
	v_fma_f32 v46, v112, v34, v35
	v_and_b32_e32 v35, 0xffff0000, v36
	v_and_b32_e32 v34, 0xffff0000, v40
	v_fma_f32 v35, v43, v35, v47
	v_fma_f32 v36, v42, v34, v35
	v_lshlrev_b32_e32 v35, 16, v37
	v_lshlrev_b32_e32 v34, 16, v41
	v_fma_f32 v35, v125, v35, v48
	v_fma_f32 v40, v124, v34, v35
	v_and_b32_e32 v35, 0xffff0000, v37
	v_and_b32_e32 v34, 0xffff0000, v41
	v_fma_f32 v35, v45, v35, v49
	v_fma_f32 v37, v44, v34, v35
	v_lshlrev_b32_e32 v35, 16, v22
	v_lshlrev_b32_e32 v34, 16, v26
	v_fma_f32 v35, v115, v35, v102
	v_fma_f32 v41, v114, v34, v35
	v_and_b32_e32 v35, 0xffff0000, v22
	v_and_b32_e32 v34, 0xffff0000, v26
	v_fma_f32 v22, v31, v35, v38
	v_fma_f32 v26, v30, v34, v22
	v_lshlrev_b32_e32 v31, 16, v23
	v_lshlrev_b32_e32 v30, 16, v27
	v_and_b32_e32 v23, 0xffff0000, v23
	v_fma_f32 v22, v127, v31, v98
	v_fma_f32 v30, v134, v30, v22
	v_and_b32_e32 v22, 0xffff0000, v27
	v_fma_f32 v23, v33, v23, v39
	v_fma_f32 v27, v135, v22, v23
	v_lshlrev_b32_e32 v23, 16, v24
	v_lshlrev_b32_e32 v22, 16, v28
	v_fma_f32 v23, v117, v23, v46
	v_fma_f32 v31, v190, v22, v23
	v_and_b32_e32 v23, 0xffff0000, v24
	v_and_b32_e32 v22, 0xffff0000, v28
	v_mul_f32_e32 v24, 0xbfb8aa3b, v41
	v_fma_f32 v19, v19, v23, v36
	v_fma_f32 v22, v191, v22, v19
	v_lshlrev_b32_e32 v19, 16, v25
	v_lshlrev_b32_e32 v18, 16, v29
	v_exp_f32_e32 v24, v24
	v_fma_f32 v19, v121, v19, v40
	v_fma_f32 v23, v192, v18, v19
	v_and_b32_e32 v19, 0xffff0000, v25
	v_and_b32_e32 v18, 0xffff0000, v29
	v_pk_mul_f32 v[18:19], v[20:21], v[18:19]
	v_mul_f32_e32 v20, 0xbfb8aa3b, v26
	v_mul_f32_e32 v21, 0xbfb8aa3b, v30
	v_exp_f32_e32 v20, v20
	v_exp_f32_e32 v21, v21
	v_add_f32_e32 v19, v19, v37
	v_add_f32_e32 v18, v18, v19
	v_add_f32_e32 v19, 1.0, v24
	v_add_f32_e32 v20, 1.0, v20
	v_add_f32_e32 v21, 1.0, v21
	v_mul_f32_e32 v24, 0xbfb8aa3b, v27
	v_rcp_f32_e32 v19, v19
	v_rcp_f32_e32 v20, v20
	v_rcp_f32_e32 v21, v21
	v_exp_f32_e32 v24, v24
	v_mul_f32_e32 v25, v41, v19
	v_mul_f32_e32 v26, v26, v20
	v_mul_f32_e32 v28, v30, v21
	v_add_f32_e32 v19, 1.0, v24
	v_mul_f32_e32 v20, 0xbfb8aa3b, v31
	v_mul_f32_e32 v21, 0xbfb8aa3b, v22
	v_rcp_f32_e32 v19, v19
	v_exp_f32_e32 v20, v20
	v_exp_f32_e32 v21, v21
	v_mul_f32_e32 v24, v27, v19
	v_add_f32_e32 v19, 1.0, v20
	v_add_f32_e32 v20, 1.0, v21
	v_mul_f32_e32 v21, 0xbfb8aa3b, v23
	v_mul_f32_e32 v27, 0xbfb8aa3b, v18
	v_exp_f32_e32 v21, v21
	v_exp_f32_e32 v27, v27
	v_rcp_f32_e32 v19, v19
	v_rcp_f32_e32 v20, v20
	v_add_f32_e32 v21, 1.0, v21
	v_add_f32_e32 v27, 1.0, v27
	v_rcp_f32_e32 v21, v21
	v_rcp_f32_e32 v27, v27
	v_mul_f32_e32 v29, v31, v19
	v_mul_f32_e32 v22, v22, v20
	v_mul_f32_e32 v23, v23, v21
	v_mul_f32_e32 v27, v18, v27
	v_cvt_pk_bf16_f32 v18, v25, v26
	v_cvt_pk_bf16_f32 v19, v28, v24
	v_cvt_pk_bf16_f32 v20, v29, v22
	v_cvt_pk_bf16_f32 v21, v23, v27
	ds_write_b128 v229, v[18:21] offset:9216
	ds_read2st64_b32 v[18:19], v107 offset0:1 offset1:3
	s_waitcnt lgkmcnt(0)
	v_sub_f32_e32 v18, v106, v18
	v_exp_f32_e32 v18, v18
	s_nop 0
	v_mul_f32_e32 v18, v19, v18
	v_mul_f32_e32 v19, v25, v18
	v_mul_f32_e32 v20, v26, v18
	v_mul_f32_e32 v21, v28, v18
	v_mul_f32_e32 v22, v22, v18
	v_mul_f32_e32 v23, v23, v18
	v_mul_f32_e32 v24, v24, v18
	v_mul_f32_e32 v25, v29, v18
	v_mul_f32_e32 v26, v27, v18
	v_cvt_pk_bf16_f32 v18, v19, v20
	v_cvt_pk_bf16_f32 v19, v21, v24
	v_cvt_pk_bf16_f32 v20, v25, v22
	v_cvt_pk_bf16_f32 v21, v23, v26
	ds_write_b128 v229, v[18:21] offset:27648
	s_waitcnt vmcnt(11)
	ds_write_b128 v224, v[66:69] offset:36864
	v_add_u32_e32 v18, 0x11800, v224
	s_waitcnt vmcnt(10)
	ds_write_b128 v18, v[70:73]
	s_waitcnt vmcnt(9)
	ds_write_b128 v224, v[74:77] offset:45568
	s_waitcnt vmcnt(8)
	ds_write_b128 v18, v[78:81] offset:8704
	s_waitcnt vmcnt(7)
	ds_write_b128 v224, v[82:85] offset:54272
	s_waitcnt vmcnt(6)
	ds_write_b128 v18, v[86:89] offset:17408
	s_waitcnt vmcnt(5)
	ds_write_b128 v224, v[90:93] offset:62976
	s_waitcnt vmcnt(4)
	ds_write_b128 v18, v[94:97] offset:26112
	s_cbranch_scc1 .LBB0_1304
	s_add_i32 s26, s92, 0x80
	s_and_b64 vcc, exec, s[10:11]
	s_cbranch_vccnz .LDT_skip
	s_mov_b32 s100, s26
	s_mov_b32 s101, s93
	s_lshl_b64 s[100:101], s[100:101], 7
	v_lshl_add_u64 v[18:19], v[176:177], 0, s[100:101]
	global_load_dword v146, v[18:19], off
	global_load_dword v147, v[18:19], off offset:128
.LDT_skip:
	s_mul_i32 s30, s26, 0x1800
	s_mul_hi_u32 s27, s26, 0x1800
	s_add_u32 s28, s84, s30
	s_addc_u32 s29, s85, s27
	v_lshl_add_u64 v[20:21], s[28:29], 0, v[138:139]
	global_load_dwordx4 v[50:53], v[20:21], off
	v_lshl_add_u64 v[18:19], s[28:29], 0, v[142:143]
	s_and_saveexec_b64 s[28:29], s[8:9]
	s_cbranch_execz .LBB0_1300
	v_lshl_add_u64 v[22:23], v[18:19], 0, v[158:159]
	global_load_dwordx4 v[58:61], v[22:23], off

; __device__ __forceinline__ float ex2(float x) { return __builtin_amdgcn_exp2f(x); }
; #define LAS __attribute__((address_space(3)))
; __device__ __forceinline__ s16x4 trr(LAS unsigned char* p) { return __builtin_bit_cast(s16x4, __builtin_amdgcn_ds_read_tr16_b64_v4i16((LAS v4i16_t*)p)); }
; __device__ __forceinline__ bf16x8 cat8(s16x4 lo, s16x4 hi) { return (bf16x8){lo[0], lo[1], lo[2], lo[3], hi[0], hi[1], hi[2], hi[3]}; }
; #define MFMA32(a, b, c) __builtin_amdgcn_mfma_f32_32x32x16_bf16((a), (b), (c), 0, 0, 0)
; __device__ __forceinline__ void ssd_stream(const Frame& F, const Args& A, int sidx) {
;     ...
;         {
;             const float eL = ex2(arr[127]);
; #pragma unroll
;             for (int i = 0; i < 16; ++i) st[i] *= eL;
; #pragma unroll
;             for (int kg = 0; kg < 2; ++kg) {
;                 s16x4 alo[4], ahi[4], blo[4], bhi[4];
; #pragma unroll
;                 for (int k4 = 0; k4 < 4; ++k4) { const int ks = 4 * kg + k4;
;                     LAS unsigned char* ba = BT + (16 * ks + 8 * hh + qq) * BS_ + (32 * nt + 16 * cb16 + 4 * pp) * 2;
;                     LAS unsigned char* xa = XST + (16 * ks + 8 * hh + qq) * XS_ + (32 * pt + 16 * cb16 + 4 * pp) * 2;
;                     alo[k4] = trr(ba); ahi[k4] = trr(ba + 4 * BS_); blo[k4] = trr(xa); bhi[k4] = trr(xa + 4 * XS_); }
;                 __builtin_amdgcn_sched_barrier(0);
; #pragma unroll
;                 for (int k4 = 0; k4 < 4; ++k4) st = MFMA32(cat8(alo[k4], ahi[k4]), cat8(blo[k4], bhi[k4]), st);
;             }
;         }
;         if (ck < 63) SSD_SCAN((LAS float*)(F.lds + L_ARR + ((ck + 1) & 1) * 1536));
.LBB0_1314:
	s_or_b64 exec, exec, s[26:27]
	v_mov_b32_e32 v19, s78
	ds_read_b32 v19, v19 offset:508
	s_waitcnt lgkmcnt(0)
	v_exp_f32_e32 v20, v19
	v_add_u32_e32 v19, v209, v211
	v_pk_mul_f32 v[16:17], v[16:17], v[20:21] op_sel_hi:[1,0]
	v_pk_mul_f32 v[14:15], v[14:15], v[20:21] op_sel_hi:[1,0]
	v_pk_mul_f32 v[12:13], v[12:13], v[20:21] op_sel_hi:[1,0]
	v_pk_mul_f32 v[10:11], v[10:11], v[20:21] op_sel_hi:[1,0]
	v_pk_mul_f32 v[8:9], v[8:9], v[20:21] op_sel_hi:[1,0]
	v_pk_mul_f32 v[6:7], v[6:7], v[20:21] op_sel_hi:[1,0]
	v_pk_mul_f32 v[4:5], v[4:5], v[20:21] op_sel_hi:[1,0]
	v_pk_mul_f32 v[2:3], v[2:3], v[20:21] op_sel_hi:[1,0]
	ds_read_b64_tr_b16 v[20:21], v19 offset:36864
	ds_read_b64_tr_b16 v[22:23], v19 offset:37952
	ds_read_b64_tr_b16 v[24:25], v227 offset:18432
	ds_read_b64_tr_b16 v[26:27], v227 offset:19008
	ds_read_b64_tr_b16 v[28:29], v19 offset:41216
	ds_read_b64_tr_b16 v[30:31], v19 offset:42304
	ds_read_b64_tr_b16 v[32:33], v227 offset:20736
	ds_read_b64_tr_b16 v[34:35], v227 offset:21312
	ds_read_b64_tr_b16 v[36:37], v19 offset:45568
	ds_read_b64_tr_b16 v[38:39], v19 offset:46656
	ds_read_b64_tr_b16 v[40:41], v227 offset:23040
	ds_read_b64_tr_b16 v[42:43], v227 offset:23616
	ds_read_b64_tr_b16 v[44:45], v19 offset:49920
	ds_read_b64_tr_b16 v[46:47], v19 offset:51008
	ds_read_b64_tr_b16 v[98:99], v227 offset:25344
	ds_read_b64_tr_b16 v[100:101], v227 offset:25920
	s_waitcnt lgkmcnt(12)
	v_mfma_f32_32x32x16_bf16 v[2:17], v[20:23], v[24:27], v[2:17]
	s_waitcnt lgkmcnt(8)
	v_mfma_f32_32x32x16_bf16 v[2:17], v[28:31], v[32:35], v[2:17]
	s_waitcnt lgkmcnt(4)
	v_mfma_f32_32x32x16_bf16 v[2:17], v[36:39], v[40:43], v[2:17]
	s_waitcnt lgkmcnt(0)
	v_mfma_f32_32x32x16_bf16 v[2:17], v[44:47], v[98:101], v[2:17]
	ds_read_b64_tr_b16 v[20:21], v19 offset:54272
	ds_read_b64_tr_b16 v[22:23], v19 offset:55360
	ds_read_b64_tr_b16 v[24:25], v227 offset:27648
	ds_read_b64_tr_b16 v[26:27], v227 offset:28224
	ds_read_b64_tr_b16 v[28:29], v19 offset:58624
	ds_read_b64_tr_b16 v[30:31], v19 offset:59712
	ds_read_b64_tr_b16 v[32:33], v227 offset:29952
	ds_read_b64_tr_b16 v[34:35], v227 offset:30528
	ds_read_b64_tr_b16 v[36:37], v19 offset:62976
	ds_read_b64_tr_b16 v[38:39], v19 offset:64064
	ds_read_b64_tr_b16 v[40:41], v227 offset:32256
	ds_read_b64_tr_b16 v[42:43], v227 offset:32832
	ds_read_b64_tr_b16 v[44:45], v228 offset:62976
	ds_read_b64_tr_b16 v[46:47], v228 offset:64064
	ds_read_b64_tr_b16 v[98:99], v227 offset:34560
	ds_read_b64_tr_b16 v[100:101], v227 offset:35136
	s_waitcnt lgkmcnt(12)
	v_mfma_f32_32x32x16_bf16 v[2:17], v[20:23], v[24:27], v[2:17]
	s_and_b64 s[26:27], s[96:97], s[60:61]
	s_andn2_b64 vcc, exec, s[26:27]
	s_waitcnt lgkmcnt(8)
	v_mfma_f32_32x32x16_bf16 v[2:17], v[28:31], v[32:35], v[2:17]
	s_waitcnt lgkmcnt(4)
	v_mfma_f32_32x32x16_bf16 v[2:17], v[36:39], v[40:43], v[2:17]
	s_waitcnt lgkmcnt(0)
	v_mfma_f32_32x32x16_bf16 v[2:17], v[44:47], v[98:101], v[2:17]
	s_cbranch_vccnz .LBB0_1292
	s_waitcnt vmcnt(14)
	v_pk_mul_f32 v[20:21], v[148:149], v[146:147]
	v_add_u32_e32 v22, -2, v202
	v_add_f32_e32 v19, v21, v20
	v_add_u32_e32 v20, -1, v202
	v_cmp_lt_i32_e32 vcc, v20, v18
	s_andn2_b32 s26, 1, s5
	s_mulk_i32 s26, 0x600
	v_cndmask_b32_e32 v20, v20, v202, vcc
	v_lshlrev_b32_e32 v20, 2, v20
	ds_bpermute_b32 v20, v20, v19
	v_cmp_lt_i32_e32 vcc, v22, v18
	s_waitcnt lgkmcnt(0)
	v_add_f32_e32 v20, v19, v20
	v_cndmask_b32_e64 v19, v20, v19, s[14:15]
	v_cndmask_b32_e32 v20, v22, v202, vcc
	v_lshlrev_b32_e32 v20, 2, v20
	ds_bpermute_b32 v20, v20, v19
	v_add_u32_e32 v22, -4, v202
	v_cmp_lt_i32_e32 vcc, v22, v18
	s_waitcnt lgkmcnt(0)
	v_add_f32_e32 v20, v19, v20
	v_cndmask_b32_e64 v19, v20, v19, s[16:17]
	v_cndmask_b32_e32 v20, v22, v202, vcc
	v_lshlrev_b32_e32 v20, 2, v20
	ds_bpermute_b32 v20, v20, v19
	v_add_u32_e32 v22, -8, v202
	v_cmp_lt_i32_e32 vcc, v22, v18
	s_waitcnt lgkmcnt(0)
	v_add_f32_e32 v20, v19, v20
	v_cndmask_b32_e64 v19, v20, v19, s[18:19]
	v_cndmask_b32_e32 v20, v22, v202, vcc
	v_lshlrev_b32_e32 v20, 2, v20
	ds_bpermute_b32 v20, v20, v19
	v_add_u32_e32 v22, -16, v202
	v_cmp_lt_i32_e32 vcc, v22, v18
	s_waitcnt lgkmcnt(0)
	v_add_f32_e32 v20, v19, v20
	v_cndmask_b32_e64 v19, v20, v19, s[20:21]
	v_cndmask_b32_e32 v20, v22, v202, vcc
	v_lshlrev_b32_e32 v20, 2, v20
	ds_bpermute_b32 v20, v20, v19
	v_subrev_u32_e32 v22, 32, v202
	v_cmp_lt_i32_e32 vcc, v22, v18
	v_add_lshl_u32 v18, v18, v203, 2
	s_waitcnt lgkmcnt(0)
	v_add_f32_e32 v20, v19, v20
	v_cndmask_b32_e64 v19, v20, v19, s[22:23]
	v_cndmask_b32_e32 v20, v22, v202, vcc
	v_lshlrev_b32_e32 v20, 2, v20
	ds_bpermute_b32 v20, v20, v19
	s_waitcnt lgkmcnt(0)
	v_add_f32_e32 v20, v19, v20
	v_cndmask_b32_e64 v19, v20, v19, s[24:25]
	ds_bpermute_b32 v20, v18, v19
	v_sub_f32_e32 v18, v19, v21
	s_waitcnt lgkmcnt(0)
	v_sub_f32_e32 v21, v20, v18
	v_sub_f32_e32 v22, v20, v19
	v_exp_f32_e32 v20, v21
	v_exp_f32_e32 v21, v22
	v_add_u32_e32 v22, s26, v220
	ds_write2st64_b64 v22, v[18:19], v[146:147] offset1:1
	v_pk_mul_f32 v[18:19], v[146:147], v[20:21]
	ds_write_b64 v22, v[18:19] offset:1024
	s_branch .LBB0_1292
